# v66 = v65 + P4 C_k^T loads issued with the Q/K burst (isolating the P4 change)
# baseline (speedup 1.0000x reference)
.LBB0_1049:
	s_or_b32 s33, s24, s72
	s_lshl_b32 s0, s33, 7
	s_or_b32 s68, s18, s0
	s_or_b32 s0, s33, s28
	s_ashr_i32 s1, s0, 31
	s_lshl_b64 s[0:1], s[0:1], 2
	s_add_u32 s0, s73, s0
	s_addc_u32 s1, s74, s1
	v_mov_b32_e32 v4, v0
	global_load_dword v211, v3, s[0:1]
	s_mov_b32 s69, s19
	s_waitcnt vmcnt(1)
	v_ashrrev_i32_e32 v70, 5, v4
	v_ashrrev_i32_e32 v71, 31, v70
	v_lshlrev_b32_e32 v2, 4, v4
	v_lshl_add_u64 v[6:7], s[68:69], 0, v[70:71]
	v_and_b32_e32 v2, 0x1f0, v2
	v_lshl_add_u64 v[8:9], s[20:21], 0, v[2:3]
	v_lshlrev_b64 v[6:7], 11, v[6:7]
	v_lshl_add_u64 v[62:63], v[8:9], 0, v[6:7]
	v_lshl_add_u64 v[10:11], s[36:37], 0, v[2:3]
	v_add_co_u32_e32 v14, vcc, s80, v62
	v_lshl_add_u64 v[64:65], v[10:11], 0, v[6:7]
	s_nop 0
	v_addc_co_u32_e32 v15, vcc, 0, v63, vcc
	v_add_co_u32_e32 v18, vcc, s80, v64
	global_load_dwordx4 v[6:9], v[62:63], off
	global_load_dwordx4 v[10:13], v[64:65], off
	v_addc_co_u32_e32 v19, vcc, 0, v65, vcc
	v_add_co_u32_e32 v22, vcc, s46, v62
	global_load_dwordx4 v[14:17], v[14:15], off
	s_nop 0
	global_load_dwordx4 v[18:21], v[18:19], off
	v_addc_co_u32_e32 v23, vcc, 0, v63, vcc
	v_add_co_u32_e32 v26, vcc, s46, v64
	s_movk_i32 s0, 0x210
	s_nop 0
	v_addc_co_u32_e32 v27, vcc, 0, v65, vcc
	v_add_co_u32_e32 v30, vcc, s81, v62
	global_load_dwordx4 v[22:25], v[22:23], off
	s_nop 0
	global_load_dwordx4 v[26:29], v[26:27], off
	v_addc_co_u32_e32 v31, vcc, 0, v63, vcc
	v_add_co_u32_e32 v34, vcc, s81, v64
	v_mul_lo_u32 v5, v70, s0
	s_nop 0
	v_addc_co_u32_e32 v35, vcc, 0, v65, vcc
	v_add_co_u32_e32 v38, vcc, s47, v62
	global_load_dwordx4 v[30:33], v[30:31], off
	s_nop 0
	global_load_dwordx4 v[34:37], v[34:35], off
	v_addc_co_u32_e32 v39, vcc, 0, v63, vcc
	v_add_co_u32_e32 v42, vcc, s47, v64
	v_add3_u32 v2, v5, v2, 0
	s_nop 0
	v_addc_co_u32_e32 v43, vcc, 0, v65, vcc
	v_add_co_u32_e32 v46, vcc, s82, v62
	global_load_dwordx4 v[38:41], v[38:39], off
	s_nop 0
	global_load_dwordx4 v[42:45], v[42:43], off
	v_addc_co_u32_e32 v47, vcc, 0, v63, vcc
	v_add_co_u32_e32 v50, vcc, s82, v64
	v_add_u32_e32 v5, 0x10800, v2
	s_nop 0
	v_addc_co_u32_e32 v51, vcc, 0, v65, vcc
	v_add_co_u32_e32 v54, vcc, s83, v62
	global_load_dwordx4 v[46:49], v[46:47], off
	s_nop 0
	global_load_dwordx4 v[50:53], v[50:51], off
	v_addc_co_u32_e32 v55, vcc, 0, v63, vcc
	v_add_co_u32_e32 v58, vcc, s83, v64
	s_cmp_lg_u32 s33, 0
	s_nop 0
	v_addc_co_u32_e32 v59, vcc, 0, v65, vcc
	v_add_co_u32_e32 v62, vcc, s84, v62
	global_load_dwordx4 v[54:57], v[54:55], off
	s_nop 0
	global_load_dwordx4 v[58:61], v[58:59], off
	v_addc_co_u32_e32 v63, vcc, 0, v63, vcc
	v_add_co_u32_e32 v66, vcc, s84, v64
	s_cselect_b64 s[24:25], -1, 0
	s_nop 0
	v_addc_co_u32_e32 v67, vcc, 0, v65, vcc
	global_load_dwordx4 v[62:65], v[62:63], off
	s_nop 0
	global_load_dwordx4 v[66:69], v[66:67], off
	s_cmp_eq_u32 s33, 0
	s_cbranch_scc1 .Lmy_p4_noct
	s_or_b32 s0, s33, s29
	s_ashr_i32 s1, s0, 31
	s_lshl_b64 s[0:1], s[0:1], 17
	s_add_u32 s0, s75, s0
	s_addc_u32 s1, s76, s1
	v_and_b32_e32 v216, 63, v4
	v_lshlrev_b32_e32 v216, 4, v216
	v_mov_b32_e32 v217, 0
	v_lshl_add_u64 v[218:219], s[0:1], 0, v[216:217]
	v_lshl_add_u64 v[218:219], v[218:219], 0, s[38:39]
	s_movk_i32 s0, 0x1000
	v_add_co_u32_e32 v220, vcc, s0, v218
	global_load_dwordx4 v[84:87], v[218:219], off
	global_load_dwordx4 v[88:91], v[218:219], off offset:1024
	global_load_dwordx4 v[92:95], v[218:219], off offset:2048
	global_load_dwordx4 v[96:99], v[218:219], off offset:3072
	v_addc_co_u32_e32 v221, vcc, 0, v219, vcc
	global_load_dwordx4 v[100:103], v[220:221], off
	global_load_dwordx4 v[104:107], v[220:221], off offset:1024
	global_load_dwordx4 v[108:111], v[220:221], off offset:2048
	global_load_dwordx4 v[112:115], v[220:221], off offset:3072
	v_add_co_u32_e32 v220, vcc, 0x2000, v218
	s_nop 1
	v_addc_co_u32_e32 v221, vcc, 0, v219, vcc
	v_add_co_u32_e32 v218, vcc, 0x3000, v218
	global_load_dwordx4 v[116:119], v[220:221], off
	global_load_dwordx4 v[120:123], v[220:221], off offset:1024
	global_load_dwordx4 v[124:127], v[220:221], off offset:2048
	global_load_dwordx4 v[128:131], v[220:221], off offset:3072
	v_addc_co_u32_e32 v219, vcc, 0, v219, vcc
	global_load_dwordx4 v[132:135], v[218:219], off
	global_load_dwordx4 v[136:139], v[218:219], off offset:1024
	global_load_dwordx4 v[140:143], v[218:219], off offset:2048
	global_load_dwordx4 v[144:147], v[218:219], off offset:3072
.Lmy_p4_noct:
	s_waitcnt vmcnt(15)
	ds_write_b128 v2, v[6:9]
	s_waitcnt vmcnt(14)
	ds_write_b128 v5, v[10:13]
	s_waitcnt vmcnt(13)
	ds_write_b128 v2, v[14:17] offset:8448
	s_waitcnt vmcnt(12)
	ds_write_b128 v5, v[18:21] offset:8448
	s_waitcnt vmcnt(11)
	ds_write_b128 v2, v[22:25] offset:16896
	s_waitcnt vmcnt(10)
	ds_write_b128 v5, v[26:29] offset:16896
	s_waitcnt vmcnt(9)
	ds_write_b128 v2, v[30:33] offset:25344
	s_waitcnt vmcnt(8)
	ds_write_b128 v5, v[34:37] offset:25344
	s_waitcnt vmcnt(7)
	ds_write_b128 v2, v[38:41] offset:33792
	s_waitcnt vmcnt(6)
	ds_write_b128 v5, v[42:45] offset:33792
	s_waitcnt vmcnt(5)
	ds_write_b128 v2, v[46:49] offset:42240
	s_waitcnt vmcnt(4)
	ds_write_b128 v5, v[50:53] offset:42240
	s_waitcnt vmcnt(3)
	ds_write_b128 v2, v[54:57] offset:50688
	s_waitcnt vmcnt(2)
	ds_write_b128 v5, v[58:61] offset:50688
	s_waitcnt vmcnt(1)
	ds_write_b128 v2, v[62:65] offset:59136
	s_waitcnt vmcnt(0)
	ds_write_b128 v5, v[66:69] offset:59136
	v_and_b32_e32 v5, 63, v4
